# attention K-tile LDS swizzle uses row&15 (was row&7): removes the 2-way bank conflict of every ds_read_b128 K-fragment read (16-lane groups, 64 banks on gfx950)
# baseline (speedup 1.0000x reference)
.LBB0_452:
	s_bfe_u32 s7, s4, 0x20001
	s_lshl_b32 s5, s6, 8
	s_and_b32 s8, s4, 1
	s_lshl_b32 s4, s7, 12
	s_and_b32 s5, s5, 0xf00
	s_or_b32 s81, s4, s5
	s_lshl_b32 s4, s81, 11
	s_add_u32 s9, s68, s4
	s_addc_u32 s10, s69, 0
	s_lshl_b32 s5, s6, 3
	s_lshl_b32 s4, s8, 9
	s_and_b32 s5, s5, 0xffffff80
	s_add_i32 s4, s5, s4
	s_ashr_i32 s5, s4, 31
	s_lshl_b64 s[48:49], s[4:5], 1
	s_add_u32 s20, s9, s48
	s_addc_u32 s21, s10, s49
	s_mul_i32 s6, s7, 0x220000
	s_add_u32 s4, s71, s6
	s_addc_u32 s5, s72, 0
	s_lshl_b32 s8, s8, 8
	s_add_u32 s4, s4, s8
	v_mov_b32_e32 v76, v0
	s_addc_u32 s5, s5, 0
	s_add_u32 s6, s73, s6
	v_ashrrev_i32_e32 v18, 4, v76
	v_lshlrev_b32_e32 v24, 3, v76
	v_add_u32_e32 v20, 32, v18
	s_addc_u32 s9, s74, 0
	v_and_b32_e32 v2, 0x78, v24
	v_ashrrev_i32_e32 v19, 31, v18
	v_ashrrev_i32_e32 v21, 31, v20
	s_add_u32 s36, s6, s8
	v_lshlrev_b32_e32 v25, 1, v2
	v_lshlrev_b64 v[50:51], 9, v[18:19]
	v_lshlrev_b64 v[10:11], 9, v[20:21]
	s_addc_u32 s37, s9, 0
	v_or_b32_e32 v52, v50, v25
	v_mov_b32_e32 v53, v51
	v_or_b32_e32 v10, v10, v25
	v_lshl_add_u64 v[2:3], s[36:37], 0, v[52:53]
	v_lshl_add_u64 v[6:7], s[36:37], 0, v[10:11]
	v_lshl_add_u64 v[12:13], s[4:5], 0, v[52:53]
	v_lshl_add_u64 v[14:15], s[4:5], 0, v[10:11]
	global_load_dwordx4 v[2:5], v[2:3], off
	s_nop 0
	global_load_dwordx4 v[6:9], v[6:7], off
	s_nop 0
	global_load_dwordx4 v[10:13], v[12:13], off
	s_nop 0
	global_load_dwordx4 v[14:17], v[14:15], off
	v_ashrrev_i32_e32 v187, 6, v76
	v_and_b32_e32 v185, 31, v76
	v_lshlrev_b32_e32 v182, 5, v187
	v_or_b32_e32 v22, v182, v185
	v_ashrrev_i32_e32 v23, 31, v22
	v_bfe_u32 v186, v76, 5, 1
	v_lshlrev_b64 v[22:23], 11, v[22:23]
	v_lshl_add_u64 v[22:23], s[20:21], 0, v[22:23]
	v_lshlrev_b32_e32 v98, 4, v186
	v_lshl_add_u64 v[22:23], v[22:23], 0, v[98:99]
	global_load_dwordx4 v[120:123], v[22:23], off
	global_load_dwordx4 v[112:115], v[22:23], off offset:32
	global_load_dwordx4 v[128:131], v[22:23], off offset:64
	global_load_dwordx4 v[124:127], v[22:23], off offset:96
	global_load_dwordx4 v[116:119], v[22:23], off offset:128
	global_load_dwordx4 v[108:111], v[22:23], off offset:160
	global_load_dwordx4 v[104:107], v[22:23], off offset:192
	global_load_dwordx4 v[100:103], v[22:23], off offset:224
	v_and_b32_e32 v21, 0xfffff0, v18
	v_lshlrev_b32_e32 v26, 1, v18
	v_lshrrev_b32_e32 v27, 1, v18
	v_and_b32_e32 v28, 3, v18
	v_and_or_b32 v21, v26, 8, v21
	v_and_or_b32 v26, v27, 4, v28
	v_and_b32_e32 v27, 0xfffff0, v20
	v_lshlrev_b32_e32 v28, 1, v20
	v_and_b32_e32 v19, 0xf0, v76
	v_bfe_u32 v24, v24, 5, 2
	v_lshlrev_b32_e32 v18, 8, v18
	v_lshlrev_b32_e32 v20, 8, v20
	v_lshrrev_b32_e32 v21, 1, v21
	v_and_or_b32 v27, v28, 8, v27
	v_bitop3_b32 v18, v25, v18, v19 bitop3:0xde
	v_bitop3_b32 v19, v25, v20, v19 bitop3:0xde
	v_or_b32_e32 v20, v21, v24
	v_lshrrev_b32_e32 v21, 1, v27
	v_lshlrev_b32_e32 v26, 6, v26
	v_and_b32_e32 v29, 48, v25
	v_add_u32_e32 v193, 0, v18
	v_add_u32_e32 v194, 0, v19
	v_lshlrev_b32_e32 v18, 9, v20
	v_or_b32_e32 v19, v21, v24
	v_or3_b32 v18, v18, v26, v29
	v_lshlrev_b32_e32 v19, 9, v19
	v_lshlrev_b32_e32 v183, 4, v76
	v_or3_b32 v19, v19, v26, v29
	v_add_u32_e32 v195, 0, v18
	v_add_u32_e32 v208, 0, v19
	s_waitcnt vmcnt(0)
	s_add_i32 s9, 0, 0x10000
	s_mov_b64 s[10:11], 0x8000
	v_and_b32_e32 v184, 63, v76
	s_cmp_lg_u32 0, -1
	s_mov_b32 s52, s53
	s_mov_b32 s54, s53
	s_mov_b32 s55, s53
	s_mov_b32 s56, s53
	s_mov_b32 s57, s53
	s_mov_b32 s58, s53
	s_waitcnt vmcnt(0)
	ds_write_b128 v195, v[2:5]
	ds_write_b128 v208, v[6:9]
	ds_write_b128 v193, v[10:13] offset:32768
	ds_write_b128 v194, v[14:17] offset:32768
	v_lshlrev_b32_e32 v14, 8, v185
	v_and_b32_e32 v15, 0xf0, v183
	v_bitop3_b32 v2, v98, v14, v15 bitop3:0xde
	v_add_u32_e32 v209, 0, v2
	s_waitcnt lgkmcnt(0)
	s_barrier
	ds_read_b128 v[2:5], v209 offset:32768
	ds_read_b128 v[6:9], v209 offset:40960
	s_waitcnt lgkmcnt(1)
	v_mfma_f32_32x32x16_bf16 v[18:33], v[2:5], v[120:123], 0
	v_or_b32_e32 v2, 32, v98
	v_bitop3_b32 v2, v2, v14, v15 bitop3:0xde
	v_add_u32_e32 v214, 0, v2
	v_lshlrev_b32_e32 v16, 3, v184
	v_and_b32_e32 v17, 0xc0, v183
	s_mov_b32 s59, s53
	s_mov_b32 s60, s53
	s_waitcnt lgkmcnt(0)
	v_mfma_f32_32x32x16_bf16 v[34:49], v[6:9], v[120:123], 0
	ds_read_b128 v[2:5], v214 offset:32768
	ds_read_b128 v[6:9], v214 offset:40960
	s_mov_b32 s61, s53
	s_mov_b32 s62, s53
	s_mov_b32 s63, s53
	s_mov_b32 s64, s53
	s_mov_b32 s65, s53
	s_mov_b32 s66, s53
	s_waitcnt lgkmcnt(1)
	v_mfma_f32_32x32x16_bf16 v[18:33], v[2:5], v[112:115], v[18:33]
	v_or_b32_e32 v2, 64, v98
	v_bitop3_b32 v2, v2, v14, v15 bitop3:0xde
	v_add_u32_e32 v213, 0, v2
	s_mov_b32 s67, s53
	s_mov_b32 s6, 1
	v_cmp_gt_u32_e64 s[40:41], 32, v184
	v_mov_b32_e32 v190, 0
	s_waitcnt lgkmcnt(0)
	v_mfma_f32_32x32x16_bf16 v[34:49], v[6:9], v[112:115], v[34:49]
	ds_read_b128 v[2:5], v213 offset:32768
	ds_read_b128 v[6:9], v213 offset:40960
	s_waitcnt lgkmcnt(1)
	v_mfma_f32_32x32x16_bf16 v[18:33], v[2:5], v[128:131], v[18:33]
	v_or_b32_e32 v2, 0x60, v98
	v_bitop3_b32 v2, v2, v14, v15 bitop3:0xde
	v_add_u32_e32 v212, 0, v2
	s_waitcnt lgkmcnt(0)
	v_mfma_f32_32x32x16_bf16 v[34:49], v[6:9], v[128:131], v[34:49]
	ds_read_b128 v[2:5], v212 offset:32768
	ds_read_b128 v[6:9], v212 offset:40960
	s_waitcnt lgkmcnt(1)
	v_mfma_f32_32x32x16_bf16 v[18:33], v[2:5], v[124:127], v[18:33]
	v_or_b32_e32 v2, 0x80, v98
	v_bitop3_b32 v2, v2, v14, v15 bitop3:0xde
	v_add_u32_e32 v211, 0, v2
	s_waitcnt lgkmcnt(0)
	v_mfma_f32_32x32x16_bf16 v[34:49], v[6:9], v[124:127], v[34:49]
	ds_read_b128 v[2:5], v211 offset:32768
	ds_read_b128 v[6:9], v211 offset:40960
	s_waitcnt lgkmcnt(1)
	v_mfma_f32_32x32x16_bf16 v[18:33], v[2:5], v[116:119], v[18:33]
	v_or_b32_e32 v2, 0xa0, v98
	v_bitop3_b32 v2, v2, v14, v15 bitop3:0xde
	v_add_u32_e32 v210, 0, v2
	ds_read_b128 v[2:5], v210 offset:32768
	s_waitcnt lgkmcnt(1)
	v_mfma_f32_32x32x16_bf16 v[34:49], v[6:9], v[116:119], v[34:49]
	v_and_b32_e32 v6, 0x3fffffc0, v76
	v_lshl_add_u32 v188, v6, 2, s9
	ds_read_b128 v[6:9], v210 offset:40960
	s_cselect_b32 s9, 0, 0
	v_lshl_add_u32 v189, v185, 2, v188
	s_waitcnt lgkmcnt(1)
	v_mfma_f32_32x32x16_bf16 v[18:33], v[2:5], v[108:111], v[18:33]
	v_lshl_add_u64 v[2:3], v[52:53], 0, s[10:11]
	s_mov_b64 s[10:11], 0xc000
	v_lshl_add_u64 v[4:5], s[36:37], 0, v[2:3]
	v_lshl_add_u64 v[10:11], v[52:53], 0, s[10:11]
	v_lshl_add_u64 v[2:3], s[4:5], 0, v[2:3]
	v_lshl_add_u64 v[12:13], s[36:37], 0, v[10:11]
	global_load_dwordx4 v[54:57], v[4:5], off
	global_load_dwordx4 v[58:61], v[12:13], off
	v_lshl_add_u64 v[4:5], s[4:5], 0, v[10:11]
	global_load_dwordx4 v[62:65], v[2:3], off
	global_load_dwordx4 v[66:69], v[4:5], off
	v_or_b32_e32 v2, 0xc0, v98
	v_bitop3_b32 v2, v2, v14, v15 bitop3:0xde
	v_add_u32_e32 v216, 0, v2
	ds_read_b128 v[2:5], v216 offset:32768
	v_lshlrev_b32_e32 v11, 1, v76
	v_and_or_b32 v10, v16, 24, v17
	s_waitcnt lgkmcnt(1)
	v_mfma_f32_32x32x16_bf16 v[34:49], v[6:9], v[108:111], v[34:49]
	v_and_b32_e32 v6, 32, v11
	v_and_b32_e32 v7, 0x100, v16
	v_or3_b32 v77, v10, v6, v7
	ds_read_b128 v[6:9], v216 offset:40960
	s_mov_b64 s[10:11], 0x14000
	v_add_u32_e32 v192, s9, v77
	s_waitcnt lgkmcnt(1)
	v_mfma_f32_32x32x16_bf16 v[18:33], v[2:5], v[104:107], v[18:33]
	v_or_b32_e32 v2, 0xe0, v98
	v_bitop3_b32 v2, v2, v14, v15 bitop3:0xde
	v_add_u32_e32 v215, 0, v2
	ds_read_b128 v[2:5], v215 offset:32768
	ds_read_b128 v[70:73], v215 offset:40960
	s_waitcnt lgkmcnt(2)
	v_mfma_f32_32x32x16_bf16 v[34:49], v[6:9], v[104:107], v[34:49]
	s_waitcnt lgkmcnt(1)
	v_mfma_f32_32x32x16_bf16 v[18:33], v[2:5], v[100:103], v[18:33]
	v_mov_b64_e32 v[2:3], s[52:53]
	v_mov_b64_e32 v[16:17], s[66:67]
	v_mov_b64_e32 v[4:5], s[54:55]
	v_mov_b64_e32 v[6:7], s[56:57]
	v_mov_b64_e32 v[8:9], s[58:59]
	v_mov_b64_e32 v[10:11], s[60:61]
	v_mov_b64_e32 v[12:13], s[62:63]
	s_waitcnt lgkmcnt(0)
	v_mfma_f32_32x32x16_bf16 v[34:49], v[70:73], v[100:103], v[34:49]
	s_nop 2
	v_max_f32_e32 v70, v19, v19
	v_max_f32_e32 v71, v18, v18
	v_max_f32_e32 v70, v71, v70
	v_max3_f32 v70, v70, v20, v21
	v_max3_f32 v70, v70, v22, v23
	v_max3_f32 v70, v70, v24, v25
	v_max3_f32 v70, v70, v26, v27
	v_max3_f32 v70, v70, v28, v29
	v_max3_f32 v70, v70, v30, v31
	v_max3_f32 v70, v70, v32, v33
	v_max3_f32 v70, v70, v34, v35
	v_max3_f32 v70, v70, v36, v37
	v_max3_f32 v70, v70, v38, v39
	v_max3_f32 v70, v70, v40, v41
	v_max3_f32 v70, v70, v42, v43
	v_max3_f32 v70, v70, v44, v45
	v_max3_f32 v70, v70, v46, v47
	v_max3_f32 v78, v70, v48, v49
	v_lshl_add_u64 v[70:71], v[52:53], 0, s[22:23]
	v_lshl_add_u64 v[72:73], s[36:37], 0, v[70:71]
	v_lshl_add_u64 v[52:53], v[52:53], 0, s[10:11]
	v_lshl_add_u64 v[70:71], s[4:5], 0, v[70:71]
	v_lshl_add_u64 v[74:75], s[36:37], 0, v[52:53]
	global_load_dwordx4 v[132:135], v[72:73], off
	global_load_dwordx4 v[140:143], v[74:75], off
	v_lshl_add_u64 v[52:53], s[4:5], 0, v[52:53]
	global_load_dwordx4 v[136:139], v[70:71], off
	global_load_dwordx4 v[144:147], v[52:53], off
	v_mov_b32_e32 v52, v78
	s_nop 1
	v_permlane32_swap_b32_e32 v78, v52
	v_max_f32_e32 v52, v52, v52
	v_max_f32_e32 v53, v78, v78
	v_max_f32_e32 v52, v53, v52
	v_add_f32_e32 v53, 0x7149f2ca, v52
	v_cmp_ge_f32_e32 vcc, s0, v53
	s_cmp_eq_u64 vcc, exec
	v_max_f32_e32 v52, 0xf149f2ca, v52
	s_cselect_b64 vcc, -1, 0
	v_cndmask_b32_e32 v168, v52, v228, vcc
	v_sub_f32_e32 v53, 0xf149f2ca, v52
	v_mul_f32_e32 v52, 0xbe0293ee, v168
	v_fmamk_f32 v18, v18, 0x3e0293ee, v52
	v_exp_f32_e32 v165, v18
	v_fmamk_f32 v18, v19, 0x3e0293ee, v52
	v_exp_f32_e32 v179, v18
	v_fmamk_f32 v18, v20, 0x3e0293ee, v52
	v_exp_f32_e32 v166, v18
	v_fmamk_f32 v18, v21, 0x3e0293ee, v52
	v_exp_f32_e32 v221, v18
	v_fmamk_f32 v18, v22, 0x3e0293ee, v52
	v_exp_f32_e32 v178, v18
	v_fmamk_f32 v18, v23, 0x3e0293ee, v52
	v_exp_f32_e32 v231, v18
	v_fmamk_f32 v18, v24, 0x3e0293ee, v52
	v_exp_f32_e32 v167, v18
	v_fmamk_f32 v18, v25, 0x3e0293ee, v52
	v_exp_f32_e32 v177, v18
	v_fmamk_f32 v18, v26, 0x3e0293ee, v52
	v_mul_f32_e32 v53, 0x3e0293ee, v53
	v_exp_f32_e32 v173, v18
	v_fmamk_f32 v18, v27, 0x3e0293ee, v52
	v_exp_f32_e32 v53, v53
	v_exp_f32_e32 v175, v18
	v_fmamk_f32 v18, v28, 0x3e0293ee, v52
	v_exp_f32_e32 v174, v18
	v_fmamk_f32 v18, v29, 0x3e0293ee, v52
	v_exp_f32_e32 v176, v18
	v_fmamk_f32 v18, v30, 0x3e0293ee, v52
	v_exp_f32_e32 v169, v18
	v_fmamk_f32 v18, v31, 0x3e0293ee, v52
	v_pk_fma_f32 v[148:149], v[48:49], s[26:27], v[52:53] op_sel_hi:[1,0,0]
	v_pk_fma_f32 v[154:155], v[46:47], s[26:27], v[52:53] op_sel_hi:[1,0,0]
	v_pk_fma_f32 v[158:159], v[44:45], s[26:27], v[52:53] op_sel_hi:[1,0,0]
	v_pk_fma_f32 v[150:151], v[42:43], s[26:27], v[52:53] op_sel_hi:[1,0,0]
	v_pk_fma_f32 v[152:153], v[40:41], s[26:27], v[52:53] op_sel_hi:[1,0,0]
	v_pk_fma_f32 v[156:157], v[38:39], s[26:27], v[52:53] op_sel_hi:[1,0,0]
	v_pk_fma_f32 v[160:161], v[36:37], s[26:27], v[52:53] op_sel_hi:[1,0,0]
	v_pk_fma_f32 v[162:163], v[34:35], s[26:27], v[52:53] op_sel_hi:[1,0,0]
	v_exp_f32_e32 v171, v18
	v_fmamk_f32 v18, v32, 0x3e0293ee, v52
	v_fmac_f32_e32 v52, 0x3e0293ee, v33
	v_and_b32_e32 v20, 15, v76
	v_exp_f32_e32 v170, v18
	v_exp_f32_e32 v172, v52
	v_mad_u64_u32 v[18:19], s[4:5], s7, v229, v[50:51]
	v_lshlrev_b32_e32 v20, 4, v20
	s_waitcnt vmcnt(4)
	v_or3_b32 v18, v18, s8, v20
	v_mov_b64_e32 v[14:15], s[64:65]
	s_waitcnt vmcnt(7)
	ds_write_b128 v195, v[54:57] offset:16384
	s_waitcnt vmcnt(6)
	ds_write_b128 v208, v[58:61] offset:16384
	s_waitcnt vmcnt(5)
	ds_write_b128 v193, v[62:65] offset:49152
	s_waitcnt vmcnt(4)
	ds_write_b128 v194, v[66:69] offset:49152
	v_cndmask_b32_e64 v217, v53, 1.0, vcc
	s_addk_i32 s9, 0x4000
	v_lshl_add_u64 v[180:181], s[46:47], 0, v[18:19]
	v_mov_b64_e32 v[64:65], v[16:17]
	v_mov_b64_e32 v[48:49], v[16:17]
	v_mov_b64_e32 v[32:33], v[16:17]
	v_add_u32_e32 v191, s9, v77
	v_mov_b64_e32 v[62:63], v[14:15]
	v_mov_b64_e32 v[60:61], v[12:13]
	v_mov_b64_e32 v[58:59], v[10:11]
	v_mov_b64_e32 v[56:57], v[8:9]
	v_mov_b64_e32 v[54:55], v[6:7]
	v_mov_b64_e32 v[52:53], v[4:5]
	v_mov_b64_e32 v[50:51], v[2:3]
	v_mov_b64_e32 v[46:47], v[14:15]
	v_mov_b64_e32 v[44:45], v[12:13]
	v_mov_b64_e32 v[42:43], v[10:11]
	v_mov_b64_e32 v[40:41], v[8:9]
	v_mov_b64_e32 v[38:39], v[6:7]
	v_mov_b64_e32 v[36:37], v[4:5]
	v_mov_b64_e32 v[34:35], v[2:3]
	v_mov_b64_e32 v[30:31], v[14:15]
	v_mov_b64_e32 v[28:29], v[12:13]
	v_mov_b64_e32 v[26:27], v[10:11]
	v_mov_b64_e32 v[24:25], v[8:9]
	v_mov_b64_e32 v[22:23], v[6:7]
	v_mov_b64_e32 v[20:21], v[4:5]
	v_mov_b64_e32 v[18:19], v[2:3]
	s_waitcnt lgkmcnt(0)
	s_barrier
